# rwkv_post_rows: all four passes issue previous-row loads together with the pass's other loads (deferred unpack)
# baseline (speedup 1.0000x reference)
; __device__ __forceinline__ void rwkv_post_rows(const Params& P, int l, int rbeg, int rend) {
;     ...
;     for (int R = rbeg + w; R < rend; R += 8) {
;         bool first; const float* st = nullptr;
;         if (R < MP) first = (R & 4095) == 0;
;         else { const int rs = R - MP; first = (rs & 15) == 0; st = P.in[5] + (size_t)(l * 16 + (rs >> 4)) * SHIFT_W; }
; #pragma unroll
;         for (int hq = 0; hq < 4; ++hq) {
;             const int col = hq * 256 + lane * 4;
;             const u16* p = proj + (size_t)R * NIN + OFF_SHIFT + col;
;             const u32x2 cr = *(const u32x2*)p, ck = *(const u32x2*)(p + 1024), cv = *(const u32x2*)(p + 2048);
;             float pr[4] = {lo_bf(cr.x), hi_bf(cr.x), lo_bf(cr.y), hi_bf(cr.y)}, pk[4] = {lo_bf(ck.x), hi_bf(ck.x), lo_bf(ck.y), hi_bf(ck.y)},
;                   pv[4] = {lo_bf(cv.x), hi_bf(cv.x), lo_bf(cv.y), hi_bf(cv.y)};
;             float qr[4], qk[4], qv[4];
;             if (!first) {
;                 const u32x2 dr = *(const u32x2*)(p - NIN), dk = *(const u32x2*)(p + 1024 - NIN), dv = *(const u32x2*)(p + 2048 - NIN);
;                 qr[0] = lo_bf(dr.x); qr[1] = hi_bf(dr.x); qr[2] = lo_bf(dr.y); qr[3] = hi_bf(dr.y);
;                 qk[0] = lo_bf(dk.x); qk[1] = hi_bf(dk.x); qk[2] = lo_bf(dk.y); qk[3] = hi_bf(dk.y);
;                 qv[0] = lo_bf(dv.x); qv[1] = hi_bf(dv.x); qv[2] = lo_bf(dv.y); qv[3] = hi_bf(dv.y);
;             } else {
; #pragma unroll
;                 for (int e = 0; e < 4; ++e) { qr[e] = st ? st[col + e] : 0.f; qk[e] = st ? st[1024 + col + e] : 0.f; qv[e] = st ? st[2048 + col + e] : 0.f; }
;             }
;             const f32x4 mr = *(const f32x4*)(mu + col), mk = *(const f32x4*)(mu + 1024 + col), mv = *(const f32x4*)(mu + 2048 + col);
;             const f32x4 a = *(const f32x4*)(aa + (size_t)R * 1024 + col);
;             const f32x4 ka = *(const f32x4*)(P.in[17] + l * 1024 + col), rk = *(const f32x4*)(P.in[18] + l * 1024 + col);
;             const f32x4 gw = *(const f32x4*)(P.in[19] + l * 1024 + col), gb = *(const f32x4*)(P.in[20] + l * 1024 + col);
;             const f32x4 y = *(const f32x4*)(yraw + (size_t)R * 1024 + col);
;             float xv[4], bon = 0.f;
; #pragma unroll
;             for (int e = 0; e < 4; ++e) {
;                 const float xr = pr[e] + (qr[e] - pr[e]) * mr[e], xk = pk[e] + (qk[e] - pk[e]) * mk[e];
.LBB0_1870:
	s_or_b64 exec, exec, s[4:5]
	global_load_dwordx4 v[12:15], v[28:29], off offset:3072
	global_load_dwordx4 v[16:19], v[42:43], off
	global_load_dwordx4 v[20:23], v[64:65], off offset:3072
	s_nop 0
	global_load_dwordx4 v[62:65], v[66:67], off offset:3072
	global_load_dwordx4 v[74:77], v[44:45], off
	global_load_dwordx4 v[80:83], v[50:51], off offset:3072
	global_load_dwordx4 v[84:87], v[52:53], off offset:3072
	global_load_dwordx4 v[88:91], v[46:47], off offset:3072
	global_load_dwordx4 v[92:95], v[48:49], off offset:3072
	global_load_dwordx2 v[102:103], v[60:61], off offset:2816
	s_waitcnt vmcnt(10)
	v_cmp_ne_u32_e32 vcc, 0, v154
	s_and_saveexec_b64 s[18:19], vcc
	v_lshlrev_b32_e32 v4, 16, v0
	v_and_b32_e32 v5, 0xffff0000, v0
	v_lshlrev_b32_e32 v6, 16, v1
	v_and_b32_e32 v7, 0xffff0000, v1
	v_lshlrev_b32_e32 v8, 16, v10
	v_and_b32_e32 v9, 0xffff0000, v10
	v_lshlrev_b32_e32 v10, 16, v11
	v_and_b32_e32 v11, 0xffff0000, v11
	v_lshlrev_b32_e32 v0, 16, v2
	v_and_b32_e32 v1, 0xffff0000, v2
	v_lshlrev_b32_e32 v2, 16, v3
	v_and_b32_e32 v3, 0xffff0000, v3
	s_mov_b64 exec, s[18:19]
	s_waitcnt vmcnt(13)
	v_and_b32_e32 v59, 0xffff0000, v72
	v_lshlrev_b32_e32 v58, 16, v72
	v_and_b32_e32 v67, 0xffff0000, v73
	v_lshlrev_b32_e32 v66, 16, v73
	s_waitcnt vmcnt(12)
	v_and_b32_e32 v73, 0xffff0000, v70
	v_lshlrev_b32_e32 v72, 16, v70
	s_waitcnt vmcnt(10)
	v_pk_add_f32 v[4:5], v[4:5], v[58:59] neg_lo:[0,1] neg_hi:[0,1]
	v_pk_add_f32 v[8:9], v[8:9], v[72:73] neg_lo:[0,1] neg_hi:[0,1]
	v_and_b32_e32 v97, 0xffff0000, v71
	v_lshlrev_b32_e32 v96, 16, v71
	v_pk_add_f32 v[6:7], v[6:7], v[66:67] neg_lo:[0,1] neg_hi:[0,1]
	v_pk_add_f32 v[10:11], v[10:11], v[96:97] neg_lo:[0,1] neg_hi:[0,1]
	v_lshlrev_b32_e32 v70, 16, v68
	v_and_b32_e32 v68, 0xffff0000, v68
	v_lshlrev_b32_e32 v98, 16, v69
	v_and_b32_e32 v100, 0xffff0000, v69
	v_mov_b32_e32 v26, v1
	v_mov_b32_e32 v104, v3
	v_mov_b32_e32 v106, v70
	v_add_u32_e32 v25, 8, v25
	v_lshl_add_u64 v[54:55], v[54:55], 0, s[10:11]
	v_lshl_add_u64 v[56:57], v[56:57], 0, s[62:63]
	s_waitcnt vmcnt(9)
	v_pk_fma_f32 v[4:5], v[4:5], v[12:13], v[58:59]
	s_waitcnt vmcnt(8)
	v_pk_fma_f32 v[8:9], v[8:9], v[16:17], v[72:73]
	s_waitcnt vmcnt(7)
	v_pk_add_f32 v[12:13], v[20:21], -1.0 op_sel_hi:[1,0]
	s_waitcnt vmcnt(6)
	v_add_f32_e32 v20, v62, v63
	v_add_f32_e32 v20, v64, v20
	v_pk_fma_f32 v[6:7], v[6:7], v[14:15], v[66:67]
	v_pk_add_f32 v[14:15], v[22:23], -1.0 op_sel_hi:[1,0]
	s_waitcnt vmcnt(2)
	v_pk_fma_f32 v[12:13], v[12:13], v[88:89], 1.0 op_sel_hi:[1,1,0]
	v_pk_fma_f32 v[10:11], v[10:11], v[18:19], v[96:97]
	v_pk_mul_f32 v[8:9], v[8:9], v[12:13]
	v_add_f32_e32 v12, v65, v20
	v_pk_fma_f32 v[14:15], v[14:15], v[90:91], 1.0 op_sel_hi:[1,1,0]
	v_pk_mul_f32 v[4:5], v[4:5], v[8:9]
	v_add_f32_dpp v8, v12, v12 quad_perm:[1,0,3,2] row_mask:0xf bank_mask:0xf bound_ctrl:1
	v_pk_mul_f32 v[10:11], v[10:11], v[14:15]
	s_waitcnt vmcnt(1)
	v_pk_mul_f32 v[4:5], v[92:93], v[4:5]
	v_add_f32_dpp v8, v8, v8 quad_perm:[2,3,0,1] row_mask:0xf bank_mask:0xf bound_ctrl:1
	v_pk_mul_f32 v[6:7], v[6:7], v[10:11]
	v_add_f32_e32 v4, 0, v4
	v_add_f32_dpp v8, v8, v8 row_half_mirror row_mask:0xf bank_mask:0xf bound_ctrl:1
	v_pk_mul_f32 v[6:7], v[94:95], v[6:7]
	v_add_f32_e32 v4, v5, v4
	v_add_f32_dpp v5, v8, v8 row_mirror row_mask:0xf bank_mask:0xf bound_ctrl:1
	v_add_f32_e32 v6, v6, v4
	v_mul_f32_e32 v4, 0x3c800000, v5
	v_add_f32_e32 v8, v7, v6
	v_pk_add_f32 v[6:7], v[62:63], v[4:5] op_sel_hi:[1,0] neg_lo:[0,1] neg_hi:[0,1]
	v_pk_add_f32 v[4:5], v[64:65], v[4:5] op_sel_hi:[1,0] neg_lo:[0,1] neg_hi:[0,1]
	v_add_f32_dpp v12, v8, v8 quad_perm:[1,0,3,2] row_mask:0xf bank_mask:0xf bound_ctrl:1
	v_pk_mul_f32 v[8:9], v[6:7], v[6:7]
	v_pk_mul_f32 v[10:11], v[4:5], v[4:5]
	v_add_f32_e32 v8, v8, v9
	v_add_f32_e32 v8, v10, v8
	v_add_f32_e32 v8, v11, v8
	v_add_f32_dpp v12, v12, v12 quad_perm:[2,3,0,1] row_mask:0xf bank_mask:0xf bound_ctrl:1
	v_mov_b32_e32 v16, v74
	v_add_f32_dpp v8, v8, v8 quad_perm:[1,0,3,2] row_mask:0xf bank_mask:0xf bound_ctrl:1
	v_mov_b32_e32 v17, v80
	v_mov_b32_e32 v107, v84
	v_add_f32_dpp v8, v8, v8 quad_perm:[2,3,0,1] row_mask:0xf bank_mask:0xf bound_ctrl:1
	v_mov_b32_e32 v80, v75
	v_mov_b32_e32 v18, v76
	v_add_f32_dpp v8, v8, v8 row_half_mirror row_mask:0xf bank_mask:0xf bound_ctrl:1
	v_mov_b32_e32 v19, v82
	v_mov_b32_e32 v82, v77
	v_add_f32_dpp v8, v8, v8 row_mirror row_mask:0xf bank_mask:0xf bound_ctrl:1
	v_fmamk_f32 v8, v8, 0x3c800000, v78
	v_mul_f32_e32 v9, 0x4b800000, v8
	v_cmp_gt_f32_e32 vcc, s16, v8
	s_nop 1
	v_cndmask_b32_e32 v8, v8, v9, vcc
	v_rsq_f32_e32 v8, v8
	v_add_f32_dpp v9, v12, v12 row_half_mirror row_mask:0xf bank_mask:0xf bound_ctrl:1
	s_nop 1
	v_mov_b32_dpp v10, v9 row_mirror row_mask:0xf bank_mask:0xf bound_ctrl:1
	v_add_f32_e32 v14, v9, v10
	v_mul_f32_e32 v9, 0x45800000, v8
	v_cndmask_b32_e32 v71, v8, v9, vcc
	v_pk_add_f32 v[0:1], v[0:1], v[70:71] neg_lo:[0,1] neg_hi:[0,1]
	v_pk_mul_f32 v[8:9], v[6:7], v[70:71] op_sel_hi:[0,1]
	v_mov_b32_e32 v69, v71
	v_mov_b32_e32 v99, v71
	v_mov_b32_e32 v101, v71
	v_mov_b32_e32 v1, v9
	v_pk_add_f32 v[8:9], v[26:27], v[68:69] neg_lo:[0,1] neg_hi:[0,1]
	v_pk_mul_f32 v[6:7], v[6:7], v[68:69]
	v_mov_b32_e32 v69, v85
	v_pk_mul_f32 v[10:11], v[4:5], v[98:99] op_sel_hi:[0,1]
	v_pk_add_f32 v[12:13], v[104:105], v[100:101] neg_lo:[0,1] neg_hi:[0,1]
	v_pk_mul_f32 v[4:5], v[4:5], v[100:101]
	v_pk_fma_f32 v[0:1], v[0:1], v[16:17], v[106:107]
	v_mov_b32_e32 v9, v7
	v_pk_add_f32 v[2:3], v[2:3], v[98:99] neg_lo:[0,1] neg_hi:[0,1]
	v_mov_b32_e32 v13, v5
	v_fmac_f32_e32 v1, v0, v14
	v_pk_fma_f32 v[4:5], v[8:9], v[80:81], v[68:69]
	s_waitcnt vmcnt(0)
	v_lshlrev_b32_e32 v0, 16, v102
	v_mov_b32_e32 v99, v86
	v_mov_b32_e32 v3, v11
	v_fmac_f32_e32 v5, v4, v14
	v_mul_f32_e32 v0, v1, v0
	v_and_b32_e32 v1, 0xffff0000, v102
	v_mov_b32_e32 v101, v87
	v_pk_fma_f32 v[2:3], v[2:3], v[18:19], v[98:99]
	v_mul_f32_e32 v1, v5, v1
	v_pk_fma_f32 v[6:7], v[12:13], v[82:83], v[100:101]
	v_fmac_f32_e32 v3, v2, v14
	v_cvt_pk_bf16_f32 v0, v0, v1
	v_lshlrev_b32_e32 v1, 16, v103
	v_cmp_le_i32_e32 vcc, s0, v25
	v_fmac_f32_e32 v7, v6, v14
	v_mul_f32_e32 v1, v3, v1
	v_and_b32_e32 v2, 0xffff0000, v103
	s_or_b64 s[8:9], vcc, s[8:9]
	v_mul_f32_e32 v2, v7, v2
	v_cvt_pk_bf16_f32 v1, v1, v2
	global_store_dwordx2 v[60:61], v[0:1], off offset:2816
	s_andn2_b64 exec, exec, s[8:9]
	s_cbranch_execz .LBB0_1986

; __device__ __forceinline__ void rwkv_post_rows(const Params& P, int l, int rbeg, int rend) {
;     ...
;             const int col = hq * 256 + lane * 4;
;             const u16* p = proj + (size_t)R * NIN + OFF_SHIFT + col;
;             const u32x2 cr = *(const u32x2*)p, ck = *(const u32x2*)(p + 1024), cv = *(const u32x2*)(p + 2048);
;             float pr[4] = {lo_bf(cr.x), hi_bf(cr.x), lo_bf(cr.y), hi_bf(cr.y)}, pk[4] = {lo_bf(ck.x), hi_bf(ck.x), lo_bf(ck.y), hi_bf(ck.y)},
;                   pv[4] = {lo_bf(cv.x), hi_bf(cv.x), lo_bf(cv.y), hi_bf(cv.y)};
;             float qr[4], qk[4], qv[4];
;             if (!first) {
;                 const u32x2 dr = *(const u32x2*)(p - NIN), dk = *(const u32x2*)(p + 1024 - NIN), dv = *(const u32x2*)(p + 2048 - NIN);
;                 qr[0] = lo_bf(dr.x); qr[1] = hi_bf(dr.x); qr[2] = lo_bf(dr.y); qr[3] = hi_bf(dr.y);
;                 qk[0] = lo_bf(dk.x); qk[1] = hi_bf(dk.x); qk[2] = lo_bf(dk.y); qk[3] = hi_bf(dk.y);
;                 qv[0] = lo_bf(dv.x); qv[1] = hi_bf(dv.x); qv[2] = lo_bf(dv.y); qv[3] = hi_bf(dv.y);
;             } else {
; #pragma unroll
;                 for (int e = 0; e < 4; ++e) { qr[e] = st ? st[col + e] : 0.f; qk[e] = st ? st[1024 + col + e] : 0.f; qv[e] = st ? st[2048 + col + e] : 0.f; }
;             }
;             const f32x4 mr = *(const f32x4*)(mu + col), mk = *(const f32x4*)(mu + 1024 + col), mv = *(const f32x4*)(mu + 2048 + col);
;             const f32x4 a = *(const f32x4*)(aa + (size_t)R * 1024 + col);
;             const f32x4 ka = *(const f32x4*)(P.in[17] + l * 1024 + col), rk = *(const f32x4*)(P.in[18] + l * 1024 + col);
;             const f32x4 gw = *(const f32x4*)(P.in[19] + l * 1024 + col), gb = *(const f32x4*)(P.in[20] + l * 1024 + col);
;             const f32x4 y = *(const f32x4*)(yraw + (size_t)R * 1024 + col);
;             float xv[4], bon = 0.f;
; #pragma unroll
;             for (int e = 0; e < 4; ++e) {
;                 const float xr = pr[e] + (qr[e] - pr[e]) * mr[e], xk = pk[e] + (qk[e] - pk[e]) * mk[e];
;                 xv[e] = pv[e] + (qv[e] - pv[e]) * mv[e];
;                 bon += xr * (xk * (1.f + (a[e] - 1.f) * ka[e])) * rk[e];
;             }
;             bon = red16(bon);
;             const float mean = red16(y[0] + y[1] + y[2] + y[3]) * (1.f / 64.f);
;             float d[4], vs = 0.f;
; #pragma unroll
.LBB0_1941:
	s_or_b64 exec, exec, s[66:67]
	global_load_dwordx4 v[80:83], v[28:29], off offset:2048
	global_load_dwordx4 v[84:87], v[38:39], off
	global_load_dwordx4 v[88:91], v[64:65], off offset:2048
	global_load_dwordx4 v[92:95], v[66:67], off offset:2048
	global_load_dwordx4 v[16:19], v[40:41], off
	global_load_dwordx4 v[12:15], v[50:51], off offset:2048
	global_load_dwordx4 v[20:23], v[52:53], off offset:2048
	global_load_dwordx4 v[96:99], v[46:47], off offset:2048
	global_load_dwordx4 v[100:103], v[48:49], off offset:2048
	global_load_dwordx2 v[116:117], v[60:61], off offset:2304
	s_waitcnt vmcnt(10)
	s_and_saveexec_b64 s[18:19], s[4:5]
	v_lshlrev_b32_e32 v4, 16, v2
	v_and_b32_e32 v5, 0xffff0000, v2
	v_lshlrev_b32_e32 v6, 16, v3
	v_and_b32_e32 v7, 0xffff0000, v3
	v_lshlrev_b32_e32 v8, 16, v0
	v_and_b32_e32 v9, 0xffff0000, v0
	v_lshlrev_b32_e32 v10, 16, v1
	v_and_b32_e32 v11, 0xffff0000, v1
	v_lshlrev_b32_e32 v0, 16, v152
	v_and_b32_e32 v1, 0xffff0000, v152
	v_lshlrev_b32_e32 v2, 16, v153
	v_and_b32_e32 v3, 0xffff0000, v153
	s_mov_b64 exec, s[18:19]
	s_waitcnt vmcnt(11)
	v_lshlrev_b32_e32 v110, 16, v68
	v_and_b32_e32 v112, 0xffff0000, v68
	v_add_co_u32_e32 v68, vcc, 0xe085000, v62
	v_lshlrev_b32_e32 v114, 16, v69
	v_and_b32_e32 v74, 0xffff0000, v69
	v_addc_co_u32_e32 v69, vcc, 0, v63, vcc
	v_add_co_u32_e32 v120, vcc, 0xe086000, v62
	v_and_b32_e32 v77, 0xffff0000, v72
	v_lshlrev_b32_e32 v76, 16, v72
	v_and_b32_e32 v105, 0xffff0000, v73
	v_lshlrev_b32_e32 v104, 16, v73
	v_and_b32_e32 v107, 0xffff0000, v70
	v_lshlrev_b32_e32 v106, 16, v70
	v_and_b32_e32 v109, 0xffff0000, v71
	v_lshlrev_b32_e32 v108, 16, v71
	v_addc_co_u32_e32 v121, vcc, 0, v63, vcc
	global_load_dwordx2 v[72:73], v[68:69], off offset:3584
	global_load_dwordx2 v[70:71], v[120:121], off offset:1536
	s_nop 0
	global_load_dwordx2 v[68:69], v[120:121], off offset:3584
	s_waitcnt vmcnt(13)
	v_pk_add_f32 v[4:5], v[4:5], v[76:77] neg_lo:[0,1] neg_hi:[0,1]
	v_pk_add_f32 v[8:9], v[8:9], v[106:107] neg_lo:[0,1] neg_hi:[0,1]
	v_pk_add_f32 v[6:7], v[6:7], v[104:105] neg_lo:[0,1] neg_hi:[0,1]
	v_pk_add_f32 v[10:11], v[10:11], v[108:109] neg_lo:[0,1] neg_hi:[0,1]
	v_mov_b32_e32 v26, v1
	v_mov_b32_e32 v118, v110
	s_waitcnt vmcnt(12)
	v_pk_fma_f32 v[4:5], v[4:5], v[80:81], v[76:77]
	s_waitcnt vmcnt(11)
	v_pk_fma_f32 v[8:9], v[8:9], v[84:85], v[106:107]
	s_waitcnt vmcnt(10)
	v_pk_add_f32 v[76:77], v[88:89], -1.0 op_sel_hi:[1,0]
	s_waitcnt vmcnt(9)
	v_add_f32_e32 v75, v92, v93
	v_pk_fma_f32 v[6:7], v[6:7], v[82:83], v[104:105]
	s_waitcnt vmcnt(7)
	v_mov_b32_e32 v83, v12
	v_mov_b32_e32 v12, v17
	s_waitcnt vmcnt(5)
	v_pk_fma_f32 v[76:77], v[76:77], v[96:97], 1.0 op_sel_hi:[1,1,0]
	v_add_f32_e32 v17, v94, v75
	v_pk_add_f32 v[80:81], v[90:91], -1.0 op_sel_hi:[1,0]
	v_pk_mul_f32 v[8:9], v[8:9], v[76:77]
	v_add_f32_e32 v17, v95, v17
	v_pk_fma_f32 v[10:11], v[10:11], v[86:87], v[108:109]
	v_pk_fma_f32 v[80:81], v[80:81], v[98:99], 1.0 op_sel_hi:[1,1,0]
	v_pk_mul_f32 v[4:5], v[4:5], v[8:9]
	v_add_f32_dpp v8, v17, v17 quad_perm:[1,0,3,2] row_mask:0xf bank_mask:0xf bound_ctrl:1
	v_pk_mul_f32 v[10:11], v[10:11], v[80:81]
	s_waitcnt vmcnt(4)
	v_pk_mul_f32 v[4:5], v[100:101], v[4:5]
	v_add_f32_dpp v8, v8, v8 quad_perm:[2,3,0,1] row_mask:0xf bank_mask:0xf bound_ctrl:1
	v_pk_mul_f32 v[6:7], v[6:7], v[10:11]
	v_add_f32_e32 v4, 0, v4
	v_add_f32_dpp v8, v8, v8 row_half_mirror row_mask:0xf bank_mask:0xf bound_ctrl:1
	v_pk_mul_f32 v[6:7], v[102:103], v[6:7]
	v_add_f32_e32 v4, v5, v4
	v_add_f32_dpp v5, v8, v8 row_mirror row_mask:0xf bank_mask:0xf bound_ctrl:1
	v_add_f32_e32 v6, v6, v4
	v_mul_f32_e32 v4, 0x3c800000, v5
	v_add_f32_e32 v8, v7, v6
	v_pk_add_f32 v[6:7], v[92:93], v[4:5] op_sel_hi:[1,0] neg_lo:[0,1] neg_hi:[0,1]
	v_pk_add_f32 v[4:5], v[94:95], v[4:5] op_sel_hi:[1,0] neg_lo:[0,1] neg_hi:[0,1]
	v_add_f32_dpp v17, v8, v8 quad_perm:[1,0,3,2] row_mask:0xf bank_mask:0xf bound_ctrl:1
	v_pk_mul_f32 v[8:9], v[6:7], v[6:7]
	v_pk_mul_f32 v[10:11], v[4:5], v[4:5]
	v_add_f32_e32 v8, v8, v9
	v_add_f32_e32 v8, v10, v8
	v_add_f32_e32 v8, v11, v8
	v_add_f32_dpp v17, v17, v17 quad_perm:[2,3,0,1] row_mask:0xf bank_mask:0xf bound_ctrl:1
	v_mov_b32_e32 v82, v16
	v_add_f32_dpp v8, v8, v8 quad_perm:[1,0,3,2] row_mask:0xf bank_mask:0xf bound_ctrl:1
	v_mov_b32_e32 v16, v18
	v_mov_b32_e32 v119, v20
	v_add_f32_dpp v8, v8, v8 quad_perm:[2,3,0,1] row_mask:0xf bank_mask:0xf bound_ctrl:1
	s_nop 1
	v_add_f32_dpp v8, v8, v8 row_half_mirror row_mask:0xf bank_mask:0xf bound_ctrl:1
	s_nop 1
	v_add_f32_dpp v8, v8, v8 row_mirror row_mask:0xf bank_mask:0xf bound_ctrl:1
	v_fmamk_f32 v8, v8, 0x3c800000, v78
	v_mul_f32_e32 v9, 0x4b800000, v8
	v_cmp_gt_f32_e32 vcc, s16, v8
	s_nop 1
	v_cndmask_b32_e32 v8, v8, v9, vcc
	v_rsq_f32_e32 v8, v8
	v_add_f32_dpp v9, v17, v17 row_half_mirror row_mask:0xf bank_mask:0xf bound_ctrl:1
	v_mov_b32_e32 v17, v14
	v_mov_b32_e32 v14, v19
	v_mov_b32_dpp v10, v9 row_mirror row_mask:0xf bank_mask:0xf bound_ctrl:1
	v_add_f32_e32 v18, v9, v10
	v_mul_f32_e32 v9, 0x45800000, v8
	v_cndmask_b32_e32 v111, v8, v9, vcc
	v_pk_add_f32 v[0:1], v[0:1], v[110:111] neg_lo:[0,1] neg_hi:[0,1]
	v_pk_mul_f32 v[8:9], v[6:7], v[110:111] op_sel_hi:[0,1]
	v_mov_b32_e32 v113, v111
	v_mov_b32_e32 v1, v9
	v_pk_add_f32 v[8:9], v[26:27], v[112:113] neg_lo:[0,1] neg_hi:[0,1]
	v_pk_mul_f32 v[6:7], v[6:7], v[112:113]
	v_pk_fma_f32 v[0:1], v[0:1], v[82:83], v[118:119]
	v_mov_b32_e32 v115, v111
	v_mov_b32_e32 v113, v21
	v_mov_b32_e32 v9, v7
	v_fmac_f32_e32 v1, v0, v18
	v_mov_b32_e32 v0, v3
	v_mov_b32_e32 v75, v111
	v_pk_add_f32 v[10:11], v[2:3], v[114:115] neg_lo:[0,1] neg_hi:[0,1]
	v_pk_mul_f32 v[20:21], v[4:5], v[114:115] op_sel_hi:[0,1]
	v_pk_fma_f32 v[6:7], v[8:9], v[12:13], v[112:113]
	v_pk_add_f32 v[2:3], v[0:1], v[74:75] neg_lo:[0,1] neg_hi:[0,1]
	s_waitcnt vmcnt(3)
	v_lshlrev_b32_e32 v0, 16, v116
	v_mov_b32_e32 v11, v21
	v_fmac_f32_e32 v7, v6, v18
	v_mov_b32_e32 v115, v22
	v_pk_mul_f32 v[4:5], v[4:5], v[74:75]
	v_mul_f32_e32 v0, v1, v0
	v_and_b32_e32 v1, 0xffff0000, v116
	v_pk_fma_f32 v[8:9], v[10:11], v[16:17], v[114:115]
	v_mov_b32_e32 v3, v5
	v_mov_b32_e32 v75, v23
	v_mul_f32_e32 v1, v7, v1
	v_fmac_f32_e32 v9, v8, v18
	v_pk_fma_f32 v[2:3], v[2:3], v[14:15], v[74:75]
	v_cvt_pk_bf16_f32 v0, v0, v1
	v_lshlrev_b32_e32 v1, 16, v117
	v_fmac_f32_e32 v3, v2, v18
	v_mul_f32_e32 v1, v9, v1
	v_and_b32_e32 v2, 0xffff0000, v117
	v_mul_f32_e32 v2, v3, v2
	v_cvt_pk_bf16_f32 v1, v1, v2
	global_store_dwordx2 v[60:61], v[0:1], off offset:2304
	v_mov_b32_e32 v154, 0
	s_and_saveexec_b64 s[18:19], s[4:5]
	s_xor_b64 s[4:5], exec, s[18:19]
	s_cbranch_execz .LBB0_1943
	v_add_co_u32_e32 v0, vcc, 0xe07e000, v62
	s_nop 1
	v_addc_co_u32_e32 v1, vcc, 0, v63, vcc
	v_add_co_u32_e32 v2, vcc, 0xe07f000, v62
	v_mov_b32_e32 v154, 1
	global_load_dwordx2 v[0:1], v[0:1], off offset:2304
	s_nop 0
	v_addc_co_u32_e32 v3, vcc, 0, v63, vcc
	global_load_dwordx2 v[10:11], v[2:3], off offset:256
	s_nop 0
	global_load_dwordx2 v[2:3], v[2:3], off offset:2304

; __device__ __forceinline__ void rwkv_post_rows(const Params& P, int l, int rbeg, int rend) {
;     ...
;     for (int R = rbeg + w; R < rend; R += 8) {
;         bool first; const float* st = nullptr;
;         if (R < MP) first = (R & 4095) == 0;
;         else { const int rs = R - MP; first = (rs & 15) == 0; st = P.in[5] + (size_t)(l * 16 + (rs >> 4)) * SHIFT_W; }
; #pragma unroll
;         for (int hq = 0; hq < 4; ++hq) {
;             const int col = hq * 256 + lane * 4;
;             const u16* p = proj + (size_t)R * NIN + OFF_SHIFT + col;
;             const u32x2 cr = *(const u32x2*)p, ck = *(const u32x2*)(p + 1024), cv = *(const u32x2*)(p + 2048);
;             float pr[4] = {lo_bf(cr.x), hi_bf(cr.x), lo_bf(cr.y), hi_bf(cr.y)}, pk[4] = {lo_bf(ck.x), hi_bf(ck.x), lo_bf(ck.y), hi_bf(ck.y)},
;                   pv[4] = {lo_bf(cv.x), hi_bf(cv.x), lo_bf(cv.y), hi_bf(cv.y)};
;             float qr[4], qk[4], qv[4];
;             if (!first) {
;                 const u32x2 dr = *(const u32x2*)(p - NIN), dk = *(const u32x2*)(p + 1024 - NIN), dv = *(const u32x2*)(p + 2048 - NIN);
;                 qr[0] = lo_bf(dr.x); qr[1] = hi_bf(dr.x); qr[2] = lo_bf(dr.y); qr[3] = hi_bf(dr.y);
;                 qk[0] = lo_bf(dk.x); qk[1] = hi_bf(dk.x); qk[2] = lo_bf(dk.y); qk[3] = hi_bf(dk.y);
;                 qv[0] = lo_bf(dv.x); qv[1] = hi_bf(dv.x); qv[2] = lo_bf(dv.y); qv[3] = hi_bf(dv.y);
;             } else {
; #pragma unroll
;                 for (int e = 0; e < 4; ++e) { qr[e] = st ? st[col + e] : 0.f; qk[e] = st ? st[1024 + col + e] : 0.f; qv[e] = st ? st[2048 + col + e] : 0.f; }
;             }
;             const f32x4 mr = *(const f32x4*)(mu + col), mk = *(const f32x4*)(mu + 1024 + col), mv = *(const f32x4*)(mu + 2048 + col);
;             const f32x4 a = *(const f32x4*)(aa + (size_t)R * 1024 + col);
;             const f32x4 ka = *(const f32x4*)(P.in[17] + l * 1024 + col), rk = *(const f32x4*)(P.in[18] + l * 1024 + col);
;             const f32x4 gw = *(const f32x4*)(P.in[19] + l * 1024 + col), gb = *(const f32x4*)(P.in[20] + l * 1024 + col);
;             const f32x4 y = *(const f32x4*)(yraw + (size_t)R * 1024 + col);
;             float xv[4], bon = 0.f;
; #pragma unroll
;             for (int e = 0; e < 4; ++e) {
;                 const float xr = pr[e] + (qr[e] - pr[e]) * mr[e], xk = pk[e] + (qk[e] - pk[e]) * mk[e];
.LBB0_4177:
	s_or_b64 exec, exec, s[6:7]
	global_load_dwordx4 v[12:15], v[46:47], off
	global_load_dwordx4 v[16:19], v[48:49], off
	global_load_dwordx4 v[20:23], v[94:95], off offset:3072
	global_load_dwordx4 v[104:107], v[96:97], off offset:3072
	global_load_dwordx4 v[110:113], v[50:51], off
	global_load_dwordx4 v[114:117], v[80:81], off
	global_load_dwordx4 v[118:121], v[82:83], off
	global_load_dwordx4 v[122:125], v[76:77], off
	global_load_dwordx4 v[126:129], v[78:79], off
	global_load_dwordx2 v[132:133], v[90:91], off offset:2816
	s_waitcnt vmcnt(10)
	v_cmp_ne_u32_e32 vcc, 0, v154
	s_and_saveexec_b64 s[4:5], vcc
	v_lshlrev_b32_e32 v4, 16, v0
	v_and_b32_e32 v5, 0xffff0000, v0
	v_lshlrev_b32_e32 v6, 16, v1
	v_and_b32_e32 v7, 0xffff0000, v1
	v_lshlrev_b32_e32 v8, 16, v10
	v_and_b32_e32 v9, 0xffff0000, v10
	v_lshlrev_b32_e32 v10, 16, v11
	v_and_b32_e32 v11, 0xffff0000, v11
	v_lshlrev_b32_e32 v0, 16, v152
	v_and_b32_e32 v1, 0xffff0000, v152
	v_lshlrev_b32_e32 v2, 16, v153
	v_and_b32_e32 v3, 0xffff0000, v153
	s_mov_b64 exec, s[4:5]
	s_waitcnt vmcnt(13)
	v_and_b32_e32 v89, 0xffff0000, v102
	v_lshlrev_b32_e32 v88, 16, v102
	s_waitcnt vmcnt(12)
	v_and_b32_e32 v95, 0xffff0000, v100
	v_lshlrev_b32_e32 v94, 16, v100
	s_waitcnt vmcnt(10)
	v_pk_add_f32 v[4:5], v[4:5], v[88:89] neg_lo:[0,1] neg_hi:[0,1]
	v_and_b32_e32 v93, 0xffff0000, v103
	v_lshlrev_b32_e32 v92, 16, v103
	v_pk_add_f32 v[8:9], v[8:9], v[94:95] neg_lo:[0,1] neg_hi:[0,1]
	v_and_b32_e32 v97, 0xffff0000, v101
	v_lshlrev_b32_e32 v96, 16, v101
	v_pk_add_f32 v[6:7], v[6:7], v[92:93] neg_lo:[0,1] neg_hi:[0,1]
	v_pk_add_f32 v[10:11], v[10:11], v[96:97] neg_lo:[0,1] neg_hi:[0,1]
	v_lshlrev_b32_e32 v100, 16, v98
	v_and_b32_e32 v98, 0xffff0000, v98
	v_lshlrev_b32_e32 v102, 16, v99
	v_and_b32_e32 v130, 0xffff0000, v99
	v_mov_b32_e32 v26, v1
	v_mov_b32_e32 v134, v3
	v_mov_b32_e32 v136, v100
	v_add_u32_e32 v25, 8, v25
	v_lshl_add_u64 v[84:85], v[84:85], 0, s[12:13]
	v_lshl_add_u64 v[86:87], v[86:87], 0, s[18:19]
	s_waitcnt vmcnt(9)
	v_pk_fma_f32 v[4:5], v[4:5], v[12:13], v[88:89]
	s_waitcnt vmcnt(8)
	v_pk_fma_f32 v[8:9], v[8:9], v[16:17], v[94:95]
	s_waitcnt vmcnt(7)
	v_pk_add_f32 v[12:13], v[20:21], -1.0 op_sel_hi:[1,0]
	s_waitcnt vmcnt(6)
	v_add_f32_e32 v20, v104, v105
	v_add_f32_e32 v20, v106, v20
	v_pk_fma_f32 v[6:7], v[6:7], v[14:15], v[92:93]
	v_pk_add_f32 v[14:15], v[22:23], -1.0 op_sel_hi:[1,0]
	s_waitcnt vmcnt(2)
	v_pk_fma_f32 v[12:13], v[12:13], v[122:123], 1.0 op_sel_hi:[1,1,0]
	v_pk_fma_f32 v[10:11], v[10:11], v[18:19], v[96:97]
	v_pk_mul_f32 v[8:9], v[8:9], v[12:13]
	v_add_f32_e32 v12, v107, v20
	v_pk_fma_f32 v[14:15], v[14:15], v[124:125], 1.0 op_sel_hi:[1,1,0]
	v_pk_mul_f32 v[4:5], v[4:5], v[8:9]
	v_add_f32_dpp v8, v12, v12 quad_perm:[1,0,3,2] row_mask:0xf bank_mask:0xf bound_ctrl:1
	v_pk_mul_f32 v[10:11], v[10:11], v[14:15]
	s_waitcnt vmcnt(1)
	v_pk_mul_f32 v[4:5], v[126:127], v[4:5]
	v_add_f32_dpp v8, v8, v8 quad_perm:[2,3,0,1] row_mask:0xf bank_mask:0xf bound_ctrl:1
	v_pk_mul_f32 v[6:7], v[6:7], v[10:11]
	v_add_f32_e32 v4, 0, v4
	v_add_f32_dpp v8, v8, v8 row_half_mirror row_mask:0xf bank_mask:0xf bound_ctrl:1
	v_pk_mul_f32 v[6:7], v[128:129], v[6:7]
	v_add_f32_e32 v4, v5, v4
	v_add_f32_dpp v5, v8, v8 row_mirror row_mask:0xf bank_mask:0xf bound_ctrl:1
	v_add_f32_e32 v6, v6, v4
	v_mul_f32_e32 v4, 0x3c800000, v5
	v_add_f32_e32 v8, v7, v6
	v_pk_add_f32 v[6:7], v[104:105], v[4:5] op_sel_hi:[1,0] neg_lo:[0,1] neg_hi:[0,1]
	v_pk_add_f32 v[4:5], v[106:107], v[4:5] op_sel_hi:[1,0] neg_lo:[0,1] neg_hi:[0,1]
	v_add_f32_dpp v12, v8, v8 quad_perm:[1,0,3,2] row_mask:0xf bank_mask:0xf bound_ctrl:1
	v_pk_mul_f32 v[8:9], v[6:7], v[6:7]
	v_pk_mul_f32 v[10:11], v[4:5], v[4:5]
	v_add_f32_e32 v8, v8, v9
	v_add_f32_e32 v8, v10, v8
	v_add_f32_e32 v8, v11, v8
	v_add_f32_dpp v12, v12, v12 quad_perm:[2,3,0,1] row_mask:0xf bank_mask:0xf bound_ctrl:1
	v_mov_b32_e32 v16, v110
	v_add_f32_dpp v8, v8, v8 quad_perm:[1,0,3,2] row_mask:0xf bank_mask:0xf bound_ctrl:1
	v_mov_b32_e32 v17, v114
	v_mov_b32_e32 v137, v118
	v_add_f32_dpp v8, v8, v8 quad_perm:[2,3,0,1] row_mask:0xf bank_mask:0xf bound_ctrl:1
	v_mov_b32_e32 v114, v111
	v_mov_b32_e32 v18, v112
	v_add_f32_dpp v8, v8, v8 row_half_mirror row_mask:0xf bank_mask:0xf bound_ctrl:1
	v_mov_b32_e32 v19, v116
	v_mov_b32_e32 v116, v113
	v_add_f32_dpp v8, v8, v8 row_mirror row_mask:0xf bank_mask:0xf bound_ctrl:1
	v_fmamk_f32 v8, v8, 0x3c800000, v108
	v_mul_f32_e32 v9, 0x4b800000, v8
	v_cmp_gt_f32_e32 vcc, s26, v8
	s_nop 1
	v_cndmask_b32_e32 v8, v8, v9, vcc
	v_rsq_f32_e32 v8, v8
	v_add_f32_dpp v9, v12, v12 row_half_mirror row_mask:0xf bank_mask:0xf bound_ctrl:1
	s_nop 1
	v_mov_b32_dpp v10, v9 row_mirror row_mask:0xf bank_mask:0xf bound_ctrl:1
	v_add_f32_e32 v14, v9, v10
	v_mul_f32_e32 v9, 0x45800000, v8
	v_cndmask_b32_e32 v101, v8, v9, vcc
	v_pk_add_f32 v[0:1], v[0:1], v[100:101] neg_lo:[0,1] neg_hi:[0,1]
	v_pk_mul_f32 v[8:9], v[6:7], v[100:101] op_sel_hi:[0,1]
	v_mov_b32_e32 v99, v101
	v_mov_b32_e32 v103, v101
	v_mov_b32_e32 v131, v101
	v_mov_b32_e32 v1, v9
	v_pk_add_f32 v[8:9], v[26:27], v[98:99] neg_lo:[0,1] neg_hi:[0,1]
	v_pk_mul_f32 v[6:7], v[6:7], v[98:99]
	v_mov_b32_e32 v99, v119
	v_pk_mul_f32 v[10:11], v[4:5], v[102:103] op_sel_hi:[0,1]
	v_pk_add_f32 v[12:13], v[134:135], v[130:131] neg_lo:[0,1] neg_hi:[0,1]
	v_pk_mul_f32 v[4:5], v[4:5], v[130:131]
	v_pk_fma_f32 v[0:1], v[0:1], v[16:17], v[136:137]
	v_mov_b32_e32 v9, v7
	v_pk_add_f32 v[2:3], v[2:3], v[102:103] neg_lo:[0,1] neg_hi:[0,1]
	v_mov_b32_e32 v13, v5
	v_fmac_f32_e32 v1, v0, v14
	v_pk_fma_f32 v[4:5], v[8:9], v[114:115], v[98:99]
	s_waitcnt vmcnt(0)
	v_lshlrev_b32_e32 v0, 16, v132
	v_mov_b32_e32 v103, v120
	v_mov_b32_e32 v3, v11
	v_fmac_f32_e32 v5, v4, v14
	v_mul_f32_e32 v0, v1, v0
	v_and_b32_e32 v1, 0xffff0000, v132
	v_mov_b32_e32 v131, v121
	v_pk_fma_f32 v[2:3], v[2:3], v[18:19], v[102:103]
	v_mul_f32_e32 v1, v5, v1
	v_pk_fma_f32 v[6:7], v[12:13], v[116:117], v[130:131]
	v_fmac_f32_e32 v3, v2, v14
	v_cvt_pk_bf16_f32 v0, v0, v1
	v_lshlrev_b32_e32 v1, 16, v133
	v_cmp_le_i32_e32 vcc, s2, v25
	v_fmac_f32_e32 v7, v6, v14
	v_mul_f32_e32 v1, v3, v1
	v_and_b32_e32 v2, 0xffff0000, v133
	s_or_b64 s[10:11], vcc, s[10:11]
	v_mul_f32_e32 v2, v7, v2
	v_cvt_pk_bf16_f32 v1, v1, v2
	global_store_dwordx2 v[90:91], v[0:1], off offset:2816
	s_andn2_b64 exec, exec, s[10:11]
	s_cbranch_execz .LBB0_4293

; __device__ __forceinline__ void rwkv_post_rows(const Params& P, int l, int rbeg, int rend) {
;     ...
;             const int col = hq * 256 + lane * 4;
;             const u16* p = proj + (size_t)R * NIN + OFF_SHIFT + col;
;             const u32x2 cr = *(const u32x2*)p, ck = *(const u32x2*)(p + 1024), cv = *(const u32x2*)(p + 2048);
;             float pr[4] = {lo_bf(cr.x), hi_bf(cr.x), lo_bf(cr.y), hi_bf(cr.y)}, pk[4] = {lo_bf(ck.x), hi_bf(ck.x), lo_bf(ck.y), hi_bf(ck.y)},
;                   pv[4] = {lo_bf(cv.x), hi_bf(cv.x), lo_bf(cv.y), hi_bf(cv.y)};
;             float qr[4], qk[4], qv[4];
;             if (!first) {
;                 const u32x2 dr = *(const u32x2*)(p - NIN), dk = *(const u32x2*)(p + 1024 - NIN), dv = *(const u32x2*)(p + 2048 - NIN);
;                 qr[0] = lo_bf(dr.x); qr[1] = hi_bf(dr.x); qr[2] = lo_bf(dr.y); qr[3] = hi_bf(dr.y);
;                 qk[0] = lo_bf(dk.x); qk[1] = hi_bf(dk.x); qk[2] = lo_bf(dk.y); qk[3] = hi_bf(dk.y);
;                 qv[0] = lo_bf(dv.x); qv[1] = hi_bf(dv.x); qv[2] = lo_bf(dv.y); qv[3] = hi_bf(dv.y);
;             } else {
; #pragma unroll
;                 for (int e = 0; e < 4; ++e) { qr[e] = st ? st[col + e] : 0.f; qk[e] = st ? st[1024 + col + e] : 0.f; qv[e] = st ? st[2048 + col + e] : 0.f; }
;             }
;             const f32x4 mr = *(const f32x4*)(mu + col), mk = *(const f32x4*)(mu + 1024 + col), mv = *(const f32x4*)(mu + 2048 + col);
;             const f32x4 a = *(const f32x4*)(aa + (size_t)R * 1024 + col);
;             const f32x4 ka = *(const f32x4*)(P.in[17] + l * 1024 + col), rk = *(const f32x4*)(P.in[18] + l * 1024 + col);
;             const f32x4 gw = *(const f32x4*)(P.in[19] + l * 1024 + col), gb = *(const f32x4*)(P.in[20] + l * 1024 + col);
;             const f32x4 y = *(const f32x4*)(yraw + (size_t)R * 1024 + col);
;             float xv[4], bon = 0.f;
; #pragma unroll
;             for (int e = 0; e < 4; ++e) {
;                 const float xr = pr[e] + (qr[e] - pr[e]) * mr[e], xk = pk[e] + (qk[e] - pk[e]) * mk[e];
;                 xv[e] = pv[e] + (qv[e] - pv[e]) * mv[e];
;                 bon += xr * (xk * (1.f + (a[e] - 1.f) * ka[e])) * rk[e];
;             }
;             bon = red16(bon);
;             const float mean = red16(y[0] + y[1] + y[2] + y[3]) * (1.f / 64.f);
;             float d[4], vs = 0.f;
; #pragma unroll
.LBB0_4248:
	s_or_b64 exec, exec, s[20:21]
	global_load_dwordx4 v[110:113], v[40:41], off
	global_load_dwordx4 v[114:117], v[42:43], off
	global_load_dwordx4 v[118:121], v[94:95], off offset:2048
	global_load_dwordx4 v[122:125], v[96:97], off offset:2048
	global_load_dwordx4 v[16:19], v[44:45], off
	global_load_dwordx4 v[12:15], v[72:73], off
	global_load_dwordx4 v[20:23], v[74:75], off
	global_load_dwordx4 v[126:129], v[68:69], off
	global_load_dwordx4 v[130:133], v[70:71], off
	global_load_dwordx2 v[146:147], v[90:91], off offset:2304
	s_waitcnt vmcnt(10)
	s_and_saveexec_b64 s[4:5], s[6:7]
	v_lshlrev_b32_e32 v4, 16, v2
	v_and_b32_e32 v5, 0xffff0000, v2
	v_lshlrev_b32_e32 v6, 16, v3
	v_and_b32_e32 v7, 0xffff0000, v3
	v_lshlrev_b32_e32 v8, 16, v10
	v_and_b32_e32 v9, 0xffff0000, v10
	v_lshlrev_b32_e32 v10, 16, v11
	v_and_b32_e32 v11, 0xffff0000, v11
	v_lshlrev_b32_e32 v0, 16, v152
	v_and_b32_e32 v1, 0xffff0000, v152
	v_lshlrev_b32_e32 v2, 16, v153
	v_and_b32_e32 v3, 0xffff0000, v153
	s_mov_b64 exec, s[4:5]
	s_waitcnt vmcnt(11)
	v_lshlrev_b32_e32 v140, 16, v98
	v_and_b32_e32 v142, 0xffff0000, v98
	v_add_co_u32_e32 v98, vcc, 0xe085000, v92
	v_lshlrev_b32_e32 v144, 16, v99
	v_and_b32_e32 v104, 0xffff0000, v99
	v_addc_co_u32_e32 v99, vcc, 0, v93, vcc
	v_add_co_u32_e32 v150, vcc, 0xe086000, v92
	v_and_b32_e32 v107, 0xffff0000, v102
	v_lshlrev_b32_e32 v106, 16, v102
	v_and_b32_e32 v135, 0xffff0000, v103
	v_lshlrev_b32_e32 v134, 16, v103
	v_and_b32_e32 v137, 0xffff0000, v100
	v_lshlrev_b32_e32 v136, 16, v100
	v_and_b32_e32 v139, 0xffff0000, v101
	v_lshlrev_b32_e32 v138, 16, v101
	v_addc_co_u32_e32 v151, vcc, 0, v93, vcc
	global_load_dwordx2 v[102:103], v[98:99], off offset:3584
	global_load_dwordx2 v[100:101], v[150:151], off offset:1536
	s_nop 0
	global_load_dwordx2 v[98:99], v[150:151], off offset:3584
	s_waitcnt vmcnt(13)
	v_pk_add_f32 v[4:5], v[4:5], v[106:107] neg_lo:[0,1] neg_hi:[0,1]
	v_pk_add_f32 v[8:9], v[8:9], v[136:137] neg_lo:[0,1] neg_hi:[0,1]
	v_pk_add_f32 v[6:7], v[6:7], v[134:135] neg_lo:[0,1] neg_hi:[0,1]
	v_pk_add_f32 v[10:11], v[10:11], v[138:139] neg_lo:[0,1] neg_hi:[0,1]
	v_mov_b32_e32 v26, v1
	v_mov_b32_e32 v148, v140
	s_waitcnt vmcnt(12)
	v_pk_fma_f32 v[4:5], v[4:5], v[110:111], v[106:107]
	s_waitcnt vmcnt(11)
	v_pk_fma_f32 v[8:9], v[8:9], v[114:115], v[136:137]
	s_waitcnt vmcnt(10)
	v_pk_add_f32 v[106:107], v[118:119], -1.0 op_sel_hi:[1,0]
	s_waitcnt vmcnt(9)
	v_add_f32_e32 v105, v122, v123
	v_pk_fma_f32 v[6:7], v[6:7], v[112:113], v[134:135]
	s_waitcnt vmcnt(7)
	v_mov_b32_e32 v113, v12
	v_mov_b32_e32 v12, v17
	s_waitcnt vmcnt(5)
	v_pk_fma_f32 v[106:107], v[106:107], v[126:127], 1.0 op_sel_hi:[1,1,0]
	v_add_f32_e32 v17, v124, v105
	v_pk_add_f32 v[110:111], v[120:121], -1.0 op_sel_hi:[1,0]
	v_pk_mul_f32 v[8:9], v[8:9], v[106:107]
	v_add_f32_e32 v17, v125, v17
	v_pk_fma_f32 v[10:11], v[10:11], v[116:117], v[138:139]
	v_pk_fma_f32 v[110:111], v[110:111], v[128:129], 1.0 op_sel_hi:[1,1,0]
	v_pk_mul_f32 v[4:5], v[4:5], v[8:9]
	v_add_f32_dpp v8, v17, v17 quad_perm:[1,0,3,2] row_mask:0xf bank_mask:0xf bound_ctrl:1
	v_pk_mul_f32 v[10:11], v[10:11], v[110:111]
	s_waitcnt vmcnt(4)
	v_pk_mul_f32 v[4:5], v[130:131], v[4:5]
	v_add_f32_dpp v8, v8, v8 quad_perm:[2,3,0,1] row_mask:0xf bank_mask:0xf bound_ctrl:1
	v_pk_mul_f32 v[6:7], v[6:7], v[10:11]
	v_add_f32_e32 v4, 0, v4
	v_add_f32_dpp v8, v8, v8 row_half_mirror row_mask:0xf bank_mask:0xf bound_ctrl:1
	v_pk_mul_f32 v[6:7], v[132:133], v[6:7]
	v_add_f32_e32 v4, v5, v4
	v_add_f32_dpp v5, v8, v8 row_mirror row_mask:0xf bank_mask:0xf bound_ctrl:1
	v_add_f32_e32 v6, v6, v4
	v_mul_f32_e32 v4, 0x3c800000, v5
	v_add_f32_e32 v8, v7, v6
	v_pk_add_f32 v[6:7], v[122:123], v[4:5] op_sel_hi:[1,0] neg_lo:[0,1] neg_hi:[0,1]
	v_pk_add_f32 v[4:5], v[124:125], v[4:5] op_sel_hi:[1,0] neg_lo:[0,1] neg_hi:[0,1]
	v_add_f32_dpp v17, v8, v8 quad_perm:[1,0,3,2] row_mask:0xf bank_mask:0xf bound_ctrl:1
	v_pk_mul_f32 v[8:9], v[6:7], v[6:7]
	v_pk_mul_f32 v[10:11], v[4:5], v[4:5]
	v_add_f32_e32 v8, v8, v9
	v_add_f32_e32 v8, v10, v8
	v_add_f32_e32 v8, v11, v8
	v_add_f32_dpp v17, v17, v17 quad_perm:[2,3,0,1] row_mask:0xf bank_mask:0xf bound_ctrl:1
	v_mov_b32_e32 v112, v16
	v_add_f32_dpp v8, v8, v8 quad_perm:[1,0,3,2] row_mask:0xf bank_mask:0xf bound_ctrl:1
	v_mov_b32_e32 v16, v18
	v_mov_b32_e32 v149, v20
	v_add_f32_dpp v8, v8, v8 quad_perm:[2,3,0,1] row_mask:0xf bank_mask:0xf bound_ctrl:1
	s_nop 1
	v_add_f32_dpp v8, v8, v8 row_half_mirror row_mask:0xf bank_mask:0xf bound_ctrl:1
	s_nop 1
	v_add_f32_dpp v8, v8, v8 row_mirror row_mask:0xf bank_mask:0xf bound_ctrl:1
	v_fmamk_f32 v8, v8, 0x3c800000, v108
	v_mul_f32_e32 v9, 0x4b800000, v8
	v_cmp_gt_f32_e32 vcc, s26, v8
	s_nop 1
	v_cndmask_b32_e32 v8, v8, v9, vcc
	v_rsq_f32_e32 v8, v8
	v_add_f32_dpp v9, v17, v17 row_half_mirror row_mask:0xf bank_mask:0xf bound_ctrl:1
	v_mov_b32_e32 v17, v14
	v_mov_b32_e32 v14, v19
	v_mov_b32_dpp v10, v9 row_mirror row_mask:0xf bank_mask:0xf bound_ctrl:1
	v_add_f32_e32 v18, v9, v10
	v_mul_f32_e32 v9, 0x45800000, v8
	v_cndmask_b32_e32 v141, v8, v9, vcc
	v_pk_add_f32 v[0:1], v[0:1], v[140:141] neg_lo:[0,1] neg_hi:[0,1]
	v_pk_mul_f32 v[8:9], v[6:7], v[140:141] op_sel_hi:[0,1]
	v_mov_b32_e32 v143, v141
	v_mov_b32_e32 v1, v9
	v_pk_add_f32 v[8:9], v[26:27], v[142:143] neg_lo:[0,1] neg_hi:[0,1]
	v_pk_mul_f32 v[6:7], v[6:7], v[142:143]
	v_pk_fma_f32 v[0:1], v[0:1], v[112:113], v[148:149]
	v_mov_b32_e32 v145, v141
	v_mov_b32_e32 v143, v21
	v_mov_b32_e32 v9, v7
	v_fmac_f32_e32 v1, v0, v18
	v_mov_b32_e32 v0, v3
	v_mov_b32_e32 v105, v141
	v_pk_add_f32 v[10:11], v[2:3], v[144:145] neg_lo:[0,1] neg_hi:[0,1]
	v_pk_mul_f32 v[20:21], v[4:5], v[144:145] op_sel_hi:[0,1]
	v_pk_fma_f32 v[6:7], v[8:9], v[12:13], v[142:143]
	v_pk_add_f32 v[2:3], v[0:1], v[104:105] neg_lo:[0,1] neg_hi:[0,1]
	s_waitcnt vmcnt(3)
	v_lshlrev_b32_e32 v0, 16, v146
	v_mov_b32_e32 v11, v21
	v_fmac_f32_e32 v7, v6, v18
	v_mov_b32_e32 v145, v22
	v_pk_mul_f32 v[4:5], v[4:5], v[104:105]
	v_mul_f32_e32 v0, v1, v0
	v_and_b32_e32 v1, 0xffff0000, v146
	v_pk_fma_f32 v[8:9], v[10:11], v[16:17], v[144:145]
	v_mov_b32_e32 v3, v5
	v_mov_b32_e32 v105, v23
	v_mul_f32_e32 v1, v7, v1
	v_fmac_f32_e32 v9, v8, v18
	v_pk_fma_f32 v[2:3], v[2:3], v[14:15], v[104:105]
	v_cvt_pk_bf16_f32 v0, v0, v1
	v_lshlrev_b32_e32 v1, 16, v147
	v_fmac_f32_e32 v3, v2, v18
	v_mul_f32_e32 v1, v9, v1
	v_and_b32_e32 v2, 0xffff0000, v147
	v_mul_f32_e32 v2, v3, v2
	v_cvt_pk_bf16_f32 v1, v1, v2
	global_store_dwordx2 v[90:91], v[0:1], off offset:2304
	v_mov_b32_e32 v154, 0
	s_and_saveexec_b64 s[4:5], s[6:7]
	s_xor_b64 s[6:7], exec, s[4:5]
	s_cbranch_execz .LBB0_4250
	v_add_co_u32_e32 v0, vcc, 0xe07e000, v92
	s_nop 1
	v_addc_co_u32_e32 v1, vcc, 0, v93, vcc
	v_add_co_u32_e32 v2, vcc, 0xe07f000, v92
	v_mov_b32_e32 v154, 1
	global_load_dwordx2 v[0:1], v[0:1], off offset:2304
	s_nop 0
	v_addc_co_u32_e32 v3, vcc, 0, v93, vcc
	global_load_dwordx2 v[10:11], v[2:3], off offset:256
	global_load_dwordx2 v[152:153], v[2:3], off offset:2304
